# v006 + batched GEMM2 mid-hook (10-slot load ring)
# speedup vs baseline: 1.5949x; 1.0069x over previous
;     __device__ __forceinline__ void mid(f32x4 (&acc)[2][2][4][2], const pg8::Unit& u, int wr, int wc, int fr, int fq) const {
;     ...
; #pragma unroll
;         for (int ai = 0; ai < 2; ++ai)
; #pragma unroll
;             for (int m = 0; m < 4; ++m) {
;                 const size_t off = (size_t)(row0 + ai * 128 + m * 16) * DM + col0;
; #pragma unroll
;                 for (int bj = 0; bj < 2; ++bj) {
;                     const u32x4 ga = *(const u32x4*)(GA + off + bj * 128), gb = *(const u32x4*)(GB + off + bj * 128);
;                     acc[ai][bj][m][0][0] *= bflo(ga.x) * __builtin_amdgcn_rcpf(bflo(gb.x)); acc[ai][bj][m][0][1] *= bfhi(ga.x) * __builtin_amdgcn_rcpf(bfhi(gb.x));
;                     acc[ai][bj][m][0][2] *= bflo(ga.y) * __builtin_amdgcn_rcpf(bflo(gb.y)); acc[ai][bj][m][0][3] *= bfhi(ga.y) * __builtin_amdgcn_rcpf(bfhi(gb.y));
;                     acc[ai][bj][m][1][0] *= bflo(ga.z) * __builtin_amdgcn_rcpf(bflo(gb.z)); acc[ai][bj][m][1][1] *= bfhi(ga.z) * __builtin_amdgcn_rcpf(bfhi(gb.z));
;                     acc[ai][bj][m][1][2] *= bflo(ga.w) * __builtin_amdgcn_rcpf(bflo(gb.w)); acc[ai][bj][m][1][3] *= bfhi(ga.w) * __builtin_amdgcn_rcpf(bfhi(gb.w));
;                     asm volatile("" : "+v"(acc[ai][bj][m][0]), "+v"(acc[ai][bj][m][1]));
;                     asm volatile("" ::: "memory");
;                 }
.LBB0_455:
	v_mov_b32_e32 v2, v146
	v_mov_b32_e32 v208, v147
	s_andn2_b64 vcc, exec, s[12:13]
	v_ashrrev_i32_e32 v3, 31, v2
	v_ashrrev_i32_e32 v209, 31, v208
	v_lshlrev_b64 v[2:3], 12, v[2:3]
	v_lshl_add_u64 v[2:3], v[2:3], 0, v[208:209]
	v_lshlrev_b64 v[2:3], 1, v[2:3]
	v_lshl_add_u64 v[204:205], s[16:17], 0, v[2:3]
	v_lshl_add_u64 v[206:207], s[14:15], 0, v[2:3]
	global_load_dwordx4 v[148:151], v[204:205], off
	global_load_dwordx4 v[152:155], v[206:207], off
	global_load_dwordx4 v[156:159], v[204:205], off offset:256
	global_load_dwordx4 v[160:163], v[206:207], off offset:256
	v_lshl_add_u64 v[208:209], v[2:3], 0, s[40:41]
	v_lshl_add_u64 v[204:205], s[16:17], 0, v[208:209]
	v_lshl_add_u64 v[206:207], s[14:15], 0, v[208:209]
	global_load_dwordx4 v[164:167], v[204:205], off
	global_load_dwordx4 v[168:171], v[206:207], off
	global_load_dwordx4 v[172:175], v[204:205], off offset:256
	global_load_dwordx4 v[176:179], v[206:207], off offset:256
	v_lshl_add_u64 v[208:209], v[2:3], 0, s[42:43]
	v_lshl_add_u64 v[204:205], s[16:17], 0, v[208:209]
	v_lshl_add_u64 v[206:207], s[14:15], 0, v[208:209]
	global_load_dwordx4 v[180:183], v[204:205], off
	global_load_dwordx4 v[184:187], v[206:207], off
	global_load_dwordx4 v[188:191], v[204:205], off offset:256
	global_load_dwordx4 v[192:195], v[206:207], off offset:256
	v_lshl_add_u64 v[208:209], v[2:3], 0, s[44:45]
	v_lshl_add_u64 v[204:205], s[16:17], 0, v[208:209]
	v_lshl_add_u64 v[206:207], s[14:15], 0, v[208:209]
	global_load_dwordx4 v[196:199], v[204:205], off
	global_load_dwordx4 v[200:203], v[206:207], off
	global_load_dwordx4 v[212:215], v[204:205], off offset:256
	global_load_dwordx4 v[216:219], v[206:207], off offset:256
	v_lshl_add_u64 v[208:209], v[2:3], 0, s[8:9]
	v_lshl_add_u64 v[204:205], s[16:17], 0, v[208:209]
	v_lshl_add_u64 v[206:207], s[14:15], 0, v[208:209]
	global_load_dwordx4 v[220:223], v[204:205], off
	global_load_dwordx4 v[224:227], v[206:207], off
	global_load_dwordx4 v[228:231], v[204:205], off offset:256
	global_load_dwordx4 v[232:235], v[206:207], off offset:256
	s_waitcnt vmcnt(18)
	v_lshlrev_b32_e32 v236, 16, v148
	v_and_b32_e32 v237, 0xffff0000, v148
	v_lshlrev_b32_e32 v238, 16, v149
	v_and_b32_e32 v239, 0xffff0000, v149
	v_lshlrev_b32_e32 v240, 16, v150
	v_and_b32_e32 v241, 0xffff0000, v150
	v_lshlrev_b32_e32 v242, 16, v151
	v_and_b32_e32 v243, 0xffff0000, v151
	v_lshlrev_b32_e32 v244, 16, v152
	v_and_b32_e32 v245, 0xffff0000, v152
	v_lshlrev_b32_e32 v246, 16, v153
	v_and_b32_e32 v247, 0xffff0000, v153
	v_lshlrev_b32_e32 v248, 16, v154
	v_and_b32_e32 v249, 0xffff0000, v154
	v_lshlrev_b32_e32 v250, 16, v155
	v_and_b32_e32 v251, 0xffff0000, v155
	v_lshl_add_u64 v[208:209], v[2:3], 0, s[46:47]
	v_lshl_add_u64 v[204:205], s[16:17], 0, v[208:209]
	v_lshl_add_u64 v[206:207], s[14:15], 0, v[208:209]
	global_load_dwordx4 v[148:151], v[204:205], off
	global_load_dwordx4 v[152:155], v[206:207], off
	v_rcp_f32_e32 v236, v236
	v_rcp_f32_e32 v237, v237
	v_rcp_f32_e32 v238, v238
	v_rcp_f32_e32 v239, v239
	v_rcp_f32_e32 v240, v240
	v_rcp_f32_e32 v241, v241
	v_rcp_f32_e32 v242, v242
	v_rcp_f32_e32 v243, v243
	v_pk_mul_f32 v[244:245], v[236:237], v[244:245]
	v_pk_mul_f32 v[246:247], v[238:239], v[246:247]
	v_pk_mul_f32 v[248:249], v[240:241], v[248:249]
	v_pk_mul_f32 v[250:251], v[242:243], v[250:251]
	v_pk_mul_f32 v[128:129], v[128:129], v[244:245]
	v_pk_mul_f32 v[130:131], v[130:131], v[246:247]
	v_pk_mul_f32 v[124:125], v[124:125], v[248:249]
	v_pk_mul_f32 v[126:127], v[126:127], v[250:251]
	s_nop 0
	s_waitcnt vmcnt(18)
	v_lshlrev_b32_e32 v236, 16, v156
	v_and_b32_e32 v237, 0xffff0000, v156
	v_lshlrev_b32_e32 v238, 16, v157
	v_and_b32_e32 v239, 0xffff0000, v157
	v_lshlrev_b32_e32 v240, 16, v158
	v_and_b32_e32 v241, 0xffff0000, v158
	v_lshlrev_b32_e32 v242, 16, v159
	v_and_b32_e32 v243, 0xffff0000, v159
	v_lshlrev_b32_e32 v244, 16, v160
	v_and_b32_e32 v245, 0xffff0000, v160
	v_lshlrev_b32_e32 v246, 16, v161
	v_and_b32_e32 v247, 0xffff0000, v161
	v_lshlrev_b32_e32 v248, 16, v162
	v_and_b32_e32 v249, 0xffff0000, v162
	v_lshlrev_b32_e32 v250, 16, v163
	v_and_b32_e32 v251, 0xffff0000, v163
	global_load_dwordx4 v[156:159], v[204:205], off offset:256
	global_load_dwordx4 v[160:163], v[206:207], off offset:256
	v_rcp_f32_e32 v236, v236
	v_rcp_f32_e32 v237, v237
	v_rcp_f32_e32 v238, v238
	v_rcp_f32_e32 v239, v239
	v_rcp_f32_e32 v240, v240
	v_rcp_f32_e32 v241, v241
	v_rcp_f32_e32 v242, v242
	v_rcp_f32_e32 v243, v243
	v_pk_mul_f32 v[244:245], v[236:237], v[244:245]
	v_pk_mul_f32 v[246:247], v[238:239], v[246:247]
	v_pk_mul_f32 v[248:249], v[240:241], v[248:249]
	v_pk_mul_f32 v[250:251], v[242:243], v[250:251]
	v_pk_mul_f32 v[120:121], v[120:121], v[244:245]
	v_pk_mul_f32 v[122:123], v[122:123], v[246:247]
	v_pk_mul_f32 v[116:117], v[116:117], v[248:249]
	v_pk_mul_f32 v[118:119], v[118:119], v[250:251]
	s_nop 0
	s_waitcnt vmcnt(18)
	v_lshlrev_b32_e32 v236, 16, v164
	v_and_b32_e32 v237, 0xffff0000, v164
	v_lshlrev_b32_e32 v238, 16, v165
	v_and_b32_e32 v239, 0xffff0000, v165
	v_lshlrev_b32_e32 v240, 16, v166
	v_and_b32_e32 v241, 0xffff0000, v166
	v_lshlrev_b32_e32 v242, 16, v167
	v_and_b32_e32 v243, 0xffff0000, v167
	v_lshlrev_b32_e32 v244, 16, v168
	v_and_b32_e32 v245, 0xffff0000, v168
	v_lshlrev_b32_e32 v246, 16, v169
	v_and_b32_e32 v247, 0xffff0000, v169
	v_lshlrev_b32_e32 v248, 16, v170
	v_and_b32_e32 v249, 0xffff0000, v170
	v_lshlrev_b32_e32 v250, 16, v171
	v_and_b32_e32 v251, 0xffff0000, v171
	v_lshl_add_u64 v[208:209], v[2:3], 0, s[48:49]
	v_lshl_add_u64 v[204:205], s[16:17], 0, v[208:209]
	v_lshl_add_u64 v[206:207], s[14:15], 0, v[208:209]
	global_load_dwordx4 v[164:167], v[204:205], off
	global_load_dwordx4 v[168:171], v[206:207], off
	v_rcp_f32_e32 v236, v236
	v_rcp_f32_e32 v237, v237
	v_rcp_f32_e32 v238, v238
	v_rcp_f32_e32 v239, v239
	v_rcp_f32_e32 v240, v240
	v_rcp_f32_e32 v241, v241
	v_rcp_f32_e32 v242, v242
	v_rcp_f32_e32 v243, v243
	v_pk_mul_f32 v[244:245], v[236:237], v[244:245]
	v_pk_mul_f32 v[246:247], v[238:239], v[246:247]
	v_pk_mul_f32 v[248:249], v[240:241], v[248:249]
	v_pk_mul_f32 v[250:251], v[242:243], v[250:251]
	v_pk_mul_f32 v[112:113], v[112:113], v[244:245]
	v_pk_mul_f32 v[114:115], v[114:115], v[246:247]
	v_pk_mul_f32 v[108:109], v[108:109], v[248:249]
	v_pk_mul_f32 v[110:111], v[110:111], v[250:251]
	s_nop 0
	s_waitcnt vmcnt(18)
;     __device__ __forceinline__ void mid(f32x4 (&acc)[2][2][4][2], const pg8::Unit& u, int wr, int wc, int fr, int fq) const {
;     ...
; #pragma unroll
;         for (int ai = 0; ai < 2; ++ai)
; #pragma unroll
;             for (int m = 0; m < 4; ++m) {
;                 const size_t off = (size_t)(row0 + ai * 128 + m * 16) * DM + col0;
; #pragma unroll
;                 for (int bj = 0; bj < 2; ++bj) {
;                     const u32x4 ga = *(const u32x4*)(GA + off + bj * 128), gb = *(const u32x4*)(GB + off + bj * 128);
;                     acc[ai][bj][m][0][0] *= bflo(ga.x) * __builtin_amdgcn_rcpf(bflo(gb.x)); acc[ai][bj][m][0][1] *= bfhi(ga.x) * __builtin_amdgcn_rcpf(bfhi(gb.x));
;                     acc[ai][bj][m][0][2] *= bflo(ga.y) * __builtin_amdgcn_rcpf(bflo(gb.y)); acc[ai][bj][m][0][3] *= bfhi(ga.y) * __builtin_amdgcn_rcpf(bfhi(gb.y));
;                     acc[ai][bj][m][1][0] *= bflo(ga.z) * __builtin_amdgcn_rcpf(bflo(gb.z)); acc[ai][bj][m][1][1] *= bfhi(ga.z) * __builtin_amdgcn_rcpf(bfhi(gb.z));
;                     acc[ai][bj][m][1][2] *= bflo(ga.w) * __builtin_amdgcn_rcpf(bflo(gb.w)); acc[ai][bj][m][1][3] *= bfhi(ga.w) * __builtin_amdgcn_rcpf(bfhi(gb.w));
;                     asm volatile("" : "+v"(acc[ai][bj][m][0]), "+v"(acc[ai][bj][m][1]));
;                     asm volatile("" ::: "memory");
;                 }
	v_lshlrev_b32_e32 v236, 16, v172
	v_and_b32_e32 v237, 0xffff0000, v172
	v_lshlrev_b32_e32 v238, 16, v173
	v_and_b32_e32 v239, 0xffff0000, v173
	v_lshlrev_b32_e32 v240, 16, v174
	v_and_b32_e32 v241, 0xffff0000, v174
	v_lshlrev_b32_e32 v242, 16, v175
	v_and_b32_e32 v243, 0xffff0000, v175
	v_lshlrev_b32_e32 v244, 16, v176
	v_and_b32_e32 v245, 0xffff0000, v176
	v_lshlrev_b32_e32 v246, 16, v177
	v_and_b32_e32 v247, 0xffff0000, v177
	v_lshlrev_b32_e32 v248, 16, v178
	v_and_b32_e32 v249, 0xffff0000, v178
	v_lshlrev_b32_e32 v250, 16, v179
	v_and_b32_e32 v251, 0xffff0000, v179
	global_load_dwordx4 v[172:175], v[204:205], off offset:256
	global_load_dwordx4 v[176:179], v[206:207], off offset:256
	v_rcp_f32_e32 v236, v236
	v_rcp_f32_e32 v237, v237
	v_rcp_f32_e32 v238, v238
	v_rcp_f32_e32 v239, v239
	v_rcp_f32_e32 v240, v240
	v_rcp_f32_e32 v241, v241
	v_rcp_f32_e32 v242, v242
	v_rcp_f32_e32 v243, v243
	v_pk_mul_f32 v[244:245], v[236:237], v[244:245]
	v_pk_mul_f32 v[246:247], v[238:239], v[246:247]
	v_pk_mul_f32 v[248:249], v[240:241], v[248:249]
	v_pk_mul_f32 v[250:251], v[242:243], v[250:251]
	v_pk_mul_f32 v[104:105], v[104:105], v[244:245]
	v_pk_mul_f32 v[106:107], v[106:107], v[246:247]
	v_pk_mul_f32 v[100:101], v[100:101], v[248:249]
	v_pk_mul_f32 v[102:103], v[102:103], v[250:251]
	s_nop 0
	s_waitcnt vmcnt(18)
	v_lshlrev_b32_e32 v236, 16, v180
	v_and_b32_e32 v237, 0xffff0000, v180
	v_lshlrev_b32_e32 v238, 16, v181
	v_and_b32_e32 v239, 0xffff0000, v181
	v_lshlrev_b32_e32 v240, 16, v182
	v_and_b32_e32 v241, 0xffff0000, v182
	v_lshlrev_b32_e32 v242, 16, v183
	v_and_b32_e32 v243, 0xffff0000, v183
	v_lshlrev_b32_e32 v244, 16, v184
	v_and_b32_e32 v245, 0xffff0000, v184
	v_lshlrev_b32_e32 v246, 16, v185
	v_and_b32_e32 v247, 0xffff0000, v185
	v_lshlrev_b32_e32 v248, 16, v186
	v_and_b32_e32 v249, 0xffff0000, v186
	v_lshlrev_b32_e32 v250, 16, v187
	v_and_b32_e32 v251, 0xffff0000, v187
	v_lshl_add_u64 v[208:209], v[2:3], 0, s[50:51]
	v_lshl_add_u64 v[204:205], s[16:17], 0, v[208:209]
	v_lshl_add_u64 v[206:207], s[14:15], 0, v[208:209]
	global_load_dwordx4 v[180:183], v[204:205], off
	global_load_dwordx4 v[184:187], v[206:207], off
	v_rcp_f32_e32 v236, v236
	v_rcp_f32_e32 v237, v237
	v_rcp_f32_e32 v238, v238
	v_rcp_f32_e32 v239, v239
	v_rcp_f32_e32 v240, v240
	v_rcp_f32_e32 v241, v241
	v_rcp_f32_e32 v242, v242
	v_rcp_f32_e32 v243, v243
	v_pk_mul_f32 v[244:245], v[236:237], v[244:245]
	v_pk_mul_f32 v[246:247], v[238:239], v[246:247]
	v_pk_mul_f32 v[248:249], v[240:241], v[248:249]
	v_pk_mul_f32 v[250:251], v[242:243], v[250:251]
	v_pk_mul_f32 v[96:97], v[96:97], v[244:245]
	v_pk_mul_f32 v[98:99], v[98:99], v[246:247]
	v_pk_mul_f32 v[92:93], v[92:93], v[248:249]
	v_pk_mul_f32 v[94:95], v[94:95], v[250:251]
	s_nop 0
	s_waitcnt vmcnt(18)
	v_lshlrev_b32_e32 v236, 16, v188
	v_and_b32_e32 v237, 0xffff0000, v188
	v_lshlrev_b32_e32 v238, 16, v189
	v_and_b32_e32 v239, 0xffff0000, v189
	v_lshlrev_b32_e32 v240, 16, v190
	v_and_b32_e32 v241, 0xffff0000, v190
	v_lshlrev_b32_e32 v242, 16, v191
	v_and_b32_e32 v243, 0xffff0000, v191
	v_lshlrev_b32_e32 v244, 16, v192
	v_and_b32_e32 v245, 0xffff0000, v192
	v_lshlrev_b32_e32 v246, 16, v193
	v_and_b32_e32 v247, 0xffff0000, v193
	v_lshlrev_b32_e32 v248, 16, v194
	v_and_b32_e32 v249, 0xffff0000, v194
	v_lshlrev_b32_e32 v250, 16, v195
	v_and_b32_e32 v251, 0xffff0000, v195
	global_load_dwordx4 v[188:191], v[204:205], off offset:256
	global_load_dwordx4 v[192:195], v[206:207], off offset:256
	v_rcp_f32_e32 v236, v236
	v_rcp_f32_e32 v237, v237
	v_rcp_f32_e32 v238, v238
	v_rcp_f32_e32 v239, v239
	v_rcp_f32_e32 v240, v240
	v_rcp_f32_e32 v241, v241
	v_rcp_f32_e32 v242, v242
	v_rcp_f32_e32 v243, v243
	v_pk_mul_f32 v[244:245], v[236:237], v[244:245]
	v_pk_mul_f32 v[246:247], v[238:239], v[246:247]
	v_pk_mul_f32 v[248:249], v[240:241], v[248:249]
	v_pk_mul_f32 v[250:251], v[242:243], v[250:251]
	v_pk_mul_f32 v[88:89], v[88:89], v[244:245]
	v_pk_mul_f32 v[90:91], v[90:91], v[246:247]
	v_pk_mul_f32 v[84:85], v[84:85], v[248:249]
	v_pk_mul_f32 v[86:87], v[86:87], v[250:251]
	s_nop 0
	s_waitcnt vmcnt(18)
	v_lshlrev_b32_e32 v236, 16, v196
	v_and_b32_e32 v237, 0xffff0000, v196
	v_lshlrev_b32_e32 v238, 16, v197
	v_and_b32_e32 v239, 0xffff0000, v197
	v_lshlrev_b32_e32 v240, 16, v198
	v_and_b32_e32 v241, 0xffff0000, v198
	v_lshlrev_b32_e32 v242, 16, v199
	v_and_b32_e32 v243, 0xffff0000, v199
	v_lshlrev_b32_e32 v244, 16, v200
	v_and_b32_e32 v245, 0xffff0000, v200
	v_lshlrev_b32_e32 v246, 16, v201
	v_and_b32_e32 v247, 0xffff0000, v201
	v_lshlrev_b32_e32 v248, 16, v202
	v_and_b32_e32 v249, 0xffff0000, v202
	v_lshlrev_b32_e32 v250, 16, v203
	v_and_b32_e32 v251, 0xffff0000, v203
	v_rcp_f32_e32 v236, v236
	v_rcp_f32_e32 v237, v237
	v_rcp_f32_e32 v238, v238
	v_rcp_f32_e32 v239, v239
	v_rcp_f32_e32 v240, v240
	v_rcp_f32_e32 v241, v241
	v_rcp_f32_e32 v242, v242
	v_rcp_f32_e32 v243, v243
	v_pk_mul_f32 v[244:245], v[236:237], v[244:245]
	v_pk_mul_f32 v[246:247], v[238:239], v[246:247]
	v_pk_mul_f32 v[248:249], v[240:241], v[248:249]
	v_pk_mul_f32 v[250:251], v[242:243], v[250:251]
	v_pk_mul_f32 v[80:81], v[80:81], v[244:245]
	v_pk_mul_f32 v[82:83], v[82:83], v[246:247]
	v_pk_mul_f32 v[76:77], v[76:77], v[248:249]
	v_pk_mul_f32 v[78:79], v[78:79], v[250:251]
	s_nop 0
	s_waitcnt vmcnt(16)
;     __device__ __forceinline__ void mid(f32x4 (&acc)[2][2][4][2], const pg8::Unit& u, int wr, int wc, int fr, int fq) const {
;     ...
; #pragma unroll
;         for (int ai = 0; ai < 2; ++ai)
; #pragma unroll
;             for (int m = 0; m < 4; ++m) {
;                 const size_t off = (size_t)(row0 + ai * 128 + m * 16) * DM + col0;
; #pragma unroll
;                 for (int bj = 0; bj < 2; ++bj) {
;                     const u32x4 ga = *(const u32x4*)(GA + off + bj * 128), gb = *(const u32x4*)(GB + off + bj * 128);
;                     acc[ai][bj][m][0][0] *= bflo(ga.x) * __builtin_amdgcn_rcpf(bflo(gb.x)); acc[ai][bj][m][0][1] *= bfhi(ga.x) * __builtin_amdgcn_rcpf(bfhi(gb.x));
;                     acc[ai][bj][m][0][2] *= bflo(ga.y) * __builtin_amdgcn_rcpf(bflo(gb.y)); acc[ai][bj][m][0][3] *= bfhi(ga.y) * __builtin_amdgcn_rcpf(bfhi(gb.y));
;                     acc[ai][bj][m][1][0] *= bflo(ga.z) * __builtin_amdgcn_rcpf(bflo(gb.z)); acc[ai][bj][m][1][1] *= bfhi(ga.z) * __builtin_amdgcn_rcpf(bfhi(gb.z));
;                     acc[ai][bj][m][1][2] *= bflo(ga.w) * __builtin_amdgcn_rcpf(bflo(gb.w)); acc[ai][bj][m][1][3] *= bfhi(ga.w) * __builtin_amdgcn_rcpf(bfhi(gb.w));
;                     asm volatile("" : "+v"(acc[ai][bj][m][0]), "+v"(acc[ai][bj][m][1]));
;                     asm volatile("" ::: "memory");
;                 }
	v_lshlrev_b32_e32 v236, 16, v212
	v_and_b32_e32 v237, 0xffff0000, v212
	v_lshlrev_b32_e32 v238, 16, v213
	v_and_b32_e32 v239, 0xffff0000, v213
	v_lshlrev_b32_e32 v240, 16, v214
	v_and_b32_e32 v241, 0xffff0000, v214
	v_lshlrev_b32_e32 v242, 16, v215
	v_and_b32_e32 v243, 0xffff0000, v215
	v_lshlrev_b32_e32 v244, 16, v216
	v_and_b32_e32 v245, 0xffff0000, v216
	v_lshlrev_b32_e32 v246, 16, v217
	v_and_b32_e32 v247, 0xffff0000, v217
	v_lshlrev_b32_e32 v248, 16, v218
	v_and_b32_e32 v249, 0xffff0000, v218
	v_lshlrev_b32_e32 v250, 16, v219
	v_and_b32_e32 v251, 0xffff0000, v219
	v_rcp_f32_e32 v236, v236
	v_rcp_f32_e32 v237, v237
	v_rcp_f32_e32 v238, v238
	v_rcp_f32_e32 v239, v239
	v_rcp_f32_e32 v240, v240
	v_rcp_f32_e32 v241, v241
	v_rcp_f32_e32 v242, v242
	v_rcp_f32_e32 v243, v243
	v_pk_mul_f32 v[244:245], v[236:237], v[244:245]
	v_pk_mul_f32 v[246:247], v[238:239], v[246:247]
	v_pk_mul_f32 v[248:249], v[240:241], v[248:249]
	v_pk_mul_f32 v[250:251], v[242:243], v[250:251]
	v_pk_mul_f32 v[72:73], v[72:73], v[244:245]
	v_pk_mul_f32 v[74:75], v[74:75], v[246:247]
	v_pk_mul_f32 v[68:69], v[68:69], v[248:249]
	v_pk_mul_f32 v[70:71], v[70:71], v[250:251]
	s_nop 0
	s_waitcnt vmcnt(14)
	v_lshlrev_b32_e32 v236, 16, v220
	v_and_b32_e32 v237, 0xffff0000, v220
	v_lshlrev_b32_e32 v238, 16, v221
	v_and_b32_e32 v239, 0xffff0000, v221
	v_lshlrev_b32_e32 v240, 16, v222
	v_and_b32_e32 v241, 0xffff0000, v222
	v_lshlrev_b32_e32 v242, 16, v223
	v_and_b32_e32 v243, 0xffff0000, v223
	v_lshlrev_b32_e32 v244, 16, v224
	v_and_b32_e32 v245, 0xffff0000, v224
	v_lshlrev_b32_e32 v246, 16, v225
	v_and_b32_e32 v247, 0xffff0000, v225
	v_lshlrev_b32_e32 v248, 16, v226
	v_and_b32_e32 v249, 0xffff0000, v226
	v_lshlrev_b32_e32 v250, 16, v227
	v_and_b32_e32 v251, 0xffff0000, v227
	v_rcp_f32_e32 v236, v236
	v_rcp_f32_e32 v237, v237
	v_rcp_f32_e32 v238, v238
	v_rcp_f32_e32 v239, v239
	v_rcp_f32_e32 v240, v240
	v_rcp_f32_e32 v241, v241
	v_rcp_f32_e32 v242, v242
	v_rcp_f32_e32 v243, v243
	v_pk_mul_f32 v[244:245], v[236:237], v[244:245]
	v_pk_mul_f32 v[246:247], v[238:239], v[246:247]
	v_pk_mul_f32 v[248:249], v[240:241], v[248:249]
	v_pk_mul_f32 v[250:251], v[242:243], v[250:251]
	v_pk_mul_f32 v[64:65], v[64:65], v[244:245]
	v_pk_mul_f32 v[66:67], v[66:67], v[246:247]
	v_pk_mul_f32 v[60:61], v[60:61], v[248:249]
	v_pk_mul_f32 v[62:63], v[62:63], v[250:251]
	s_nop 0
	s_waitcnt vmcnt(12)
	v_lshlrev_b32_e32 v236, 16, v228
	v_and_b32_e32 v237, 0xffff0000, v228
	v_lshlrev_b32_e32 v238, 16, v229
	v_and_b32_e32 v239, 0xffff0000, v229
	v_lshlrev_b32_e32 v240, 16, v230
	v_and_b32_e32 v241, 0xffff0000, v230
	v_lshlrev_b32_e32 v242, 16, v231
	v_and_b32_e32 v243, 0xffff0000, v231
	v_lshlrev_b32_e32 v244, 16, v232
	v_and_b32_e32 v245, 0xffff0000, v232
	v_lshlrev_b32_e32 v246, 16, v233
	v_and_b32_e32 v247, 0xffff0000, v233
	v_lshlrev_b32_e32 v248, 16, v234
	v_and_b32_e32 v249, 0xffff0000, v234
	v_lshlrev_b32_e32 v250, 16, v235
	v_and_b32_e32 v251, 0xffff0000, v235
	v_rcp_f32_e32 v236, v236
	v_rcp_f32_e32 v237, v237
	v_rcp_f32_e32 v238, v238
	v_rcp_f32_e32 v239, v239
	v_rcp_f32_e32 v240, v240
	v_rcp_f32_e32 v241, v241
	v_rcp_f32_e32 v242, v242
	v_rcp_f32_e32 v243, v243
	v_pk_mul_f32 v[244:245], v[236:237], v[244:245]
	v_pk_mul_f32 v[246:247], v[238:239], v[246:247]
	v_pk_mul_f32 v[248:249], v[240:241], v[248:249]
	v_pk_mul_f32 v[250:251], v[242:243], v[250:251]
	v_pk_mul_f32 v[56:57], v[56:57], v[244:245]
	v_pk_mul_f32 v[58:59], v[58:59], v[246:247]
	v_pk_mul_f32 v[52:53], v[52:53], v[248:249]
	v_pk_mul_f32 v[54:55], v[54:55], v[250:251]
	s_nop 0
	s_waitcnt vmcnt(10)
	v_lshlrev_b32_e32 v236, 16, v148
	v_and_b32_e32 v237, 0xffff0000, v148
	v_lshlrev_b32_e32 v238, 16, v149
	v_and_b32_e32 v239, 0xffff0000, v149
	v_lshlrev_b32_e32 v240, 16, v150
	v_and_b32_e32 v241, 0xffff0000, v150
	v_lshlrev_b32_e32 v242, 16, v151
	v_and_b32_e32 v243, 0xffff0000, v151
	v_lshlrev_b32_e32 v244, 16, v152
	v_and_b32_e32 v245, 0xffff0000, v152
	v_lshlrev_b32_e32 v246, 16, v153
	v_and_b32_e32 v247, 0xffff0000, v153
	v_lshlrev_b32_e32 v248, 16, v154
	v_and_b32_e32 v249, 0xffff0000, v154
	v_lshlrev_b32_e32 v250, 16, v155
	v_and_b32_e32 v251, 0xffff0000, v155
	v_rcp_f32_e32 v236, v236
	v_rcp_f32_e32 v237, v237
	v_rcp_f32_e32 v238, v238
	v_rcp_f32_e32 v239, v239
	v_rcp_f32_e32 v240, v240
	v_rcp_f32_e32 v241, v241
	v_rcp_f32_e32 v242, v242
	v_rcp_f32_e32 v243, v243
	v_pk_mul_f32 v[244:245], v[236:237], v[244:245]
	v_pk_mul_f32 v[246:247], v[238:239], v[246:247]
	v_pk_mul_f32 v[248:249], v[240:241], v[248:249]
	v_pk_mul_f32 v[250:251], v[242:243], v[250:251]
	v_pk_mul_f32 v[48:49], v[48:49], v[244:245]
	v_pk_mul_f32 v[50:51], v[50:51], v[246:247]
	v_pk_mul_f32 v[44:45], v[44:45], v[248:249]
	v_pk_mul_f32 v[46:47], v[46:47], v[250:251]
	s_nop 0
	s_waitcnt vmcnt(8)
	v_lshlrev_b32_e32 v236, 16, v156
	v_and_b32_e32 v237, 0xffff0000, v156
	v_lshlrev_b32_e32 v238, 16, v157
	v_and_b32_e32 v239, 0xffff0000, v157
	v_lshlrev_b32_e32 v240, 16, v158
	v_and_b32_e32 v241, 0xffff0000, v158
	v_lshlrev_b32_e32 v242, 16, v159
	v_and_b32_e32 v243, 0xffff0000, v159
	v_lshlrev_b32_e32 v244, 16, v160
	v_and_b32_e32 v245, 0xffff0000, v160
	v_lshlrev_b32_e32 v246, 16, v161
	v_and_b32_e32 v247, 0xffff0000, v161
	v_lshlrev_b32_e32 v248, 16, v162
	v_and_b32_e32 v249, 0xffff0000, v162
	v_lshlrev_b32_e32 v250, 16, v163
	v_and_b32_e32 v251, 0xffff0000, v163
	v_rcp_f32_e32 v236, v236
	v_rcp_f32_e32 v237, v237
	v_rcp_f32_e32 v238, v238
	v_rcp_f32_e32 v239, v239
	v_rcp_f32_e32 v240, v240
	v_rcp_f32_e32 v241, v241
	v_rcp_f32_e32 v242, v242
	v_rcp_f32_e32 v243, v243
	v_pk_mul_f32 v[244:245], v[236:237], v[244:245]
	v_pk_mul_f32 v[246:247], v[238:239], v[246:247]
	v_pk_mul_f32 v[248:249], v[240:241], v[248:249]
	v_pk_mul_f32 v[250:251], v[242:243], v[250:251]
	v_pk_mul_f32 v[40:41], v[40:41], v[244:245]
	v_pk_mul_f32 v[42:43], v[42:43], v[246:247]
	v_pk_mul_f32 v[36:37], v[36:37], v[248:249]
	v_pk_mul_f32 v[38:39], v[38:39], v[250:251]
	s_nop 0
	s_waitcnt vmcnt(6)
;     __device__ __forceinline__ void mid(f32x4 (&acc)[2][2][4][2], const pg8::Unit& u, int wr, int wc, int fr, int fq) const {
;     ...
; #pragma unroll
;         for (int ai = 0; ai < 2; ++ai)
; #pragma unroll
;             for (int m = 0; m < 4; ++m) {
;                 const size_t off = (size_t)(row0 + ai * 128 + m * 16) * DM + col0;
; #pragma unroll
;                 for (int bj = 0; bj < 2; ++bj) {
;                     const u32x4 ga = *(const u32x4*)(GA + off + bj * 128), gb = *(const u32x4*)(GB + off + bj * 128);
;                     acc[ai][bj][m][0][0] *= bflo(ga.x) * __builtin_amdgcn_rcpf(bflo(gb.x)); acc[ai][bj][m][0][1] *= bfhi(ga.x) * __builtin_amdgcn_rcpf(bfhi(gb.x));
;                     acc[ai][bj][m][0][2] *= bflo(ga.y) * __builtin_amdgcn_rcpf(bflo(gb.y)); acc[ai][bj][m][0][3] *= bfhi(ga.y) * __builtin_amdgcn_rcpf(bfhi(gb.y));
;                     acc[ai][bj][m][1][0] *= bflo(ga.z) * __builtin_amdgcn_rcpf(bflo(gb.z)); acc[ai][bj][m][1][1] *= bfhi(ga.z) * __builtin_amdgcn_rcpf(bfhi(gb.z));
;                     acc[ai][bj][m][1][2] *= bflo(ga.w) * __builtin_amdgcn_rcpf(bflo(gb.w)); acc[ai][bj][m][1][3] *= bfhi(ga.w) * __builtin_amdgcn_rcpf(bfhi(gb.w));
;                     asm volatile("" : "+v"(acc[ai][bj][m][0]), "+v"(acc[ai][bj][m][1]));
;                     asm volatile("" ::: "memory");
;                 }
	v_lshlrev_b32_e32 v236, 16, v164
	v_and_b32_e32 v237, 0xffff0000, v164
	v_lshlrev_b32_e32 v238, 16, v165
	v_and_b32_e32 v239, 0xffff0000, v165
	v_lshlrev_b32_e32 v240, 16, v166
	v_and_b32_e32 v241, 0xffff0000, v166
	v_lshlrev_b32_e32 v242, 16, v167
	v_and_b32_e32 v243, 0xffff0000, v167
	v_lshlrev_b32_e32 v244, 16, v168
	v_and_b32_e32 v245, 0xffff0000, v168
	v_lshlrev_b32_e32 v246, 16, v169
	v_and_b32_e32 v247, 0xffff0000, v169
	v_lshlrev_b32_e32 v248, 16, v170
	v_and_b32_e32 v249, 0xffff0000, v170
	v_lshlrev_b32_e32 v250, 16, v171
	v_and_b32_e32 v251, 0xffff0000, v171
	v_rcp_f32_e32 v236, v236
	v_rcp_f32_e32 v237, v237
	v_rcp_f32_e32 v238, v238
	v_rcp_f32_e32 v239, v239
	v_rcp_f32_e32 v240, v240
	v_rcp_f32_e32 v241, v241
	v_rcp_f32_e32 v242, v242
	v_rcp_f32_e32 v243, v243
	v_pk_mul_f32 v[244:245], v[236:237], v[244:245]
	v_pk_mul_f32 v[246:247], v[238:239], v[246:247]
	v_pk_mul_f32 v[248:249], v[240:241], v[248:249]
	v_pk_mul_f32 v[250:251], v[242:243], v[250:251]
	v_pk_mul_f32 v[32:33], v[32:33], v[244:245]
	v_pk_mul_f32 v[34:35], v[34:35], v[246:247]
	v_pk_mul_f32 v[28:29], v[28:29], v[248:249]
	v_pk_mul_f32 v[30:31], v[30:31], v[250:251]
	s_nop 0
	s_waitcnt vmcnt(4)
	v_lshlrev_b32_e32 v236, 16, v172
	v_and_b32_e32 v237, 0xffff0000, v172
	v_lshlrev_b32_e32 v238, 16, v173
	v_and_b32_e32 v239, 0xffff0000, v173
	v_lshlrev_b32_e32 v240, 16, v174
	v_and_b32_e32 v241, 0xffff0000, v174
	v_lshlrev_b32_e32 v242, 16, v175
	v_and_b32_e32 v243, 0xffff0000, v175
	v_lshlrev_b32_e32 v244, 16, v176
	v_and_b32_e32 v245, 0xffff0000, v176
	v_lshlrev_b32_e32 v246, 16, v177
	v_and_b32_e32 v247, 0xffff0000, v177
	v_lshlrev_b32_e32 v248, 16, v178
	v_and_b32_e32 v249, 0xffff0000, v178
	v_lshlrev_b32_e32 v250, 16, v179
	v_and_b32_e32 v251, 0xffff0000, v179
	v_rcp_f32_e32 v236, v236
	v_rcp_f32_e32 v237, v237
	v_rcp_f32_e32 v238, v238
	v_rcp_f32_e32 v239, v239
	v_rcp_f32_e32 v240, v240
	v_rcp_f32_e32 v241, v241
	v_rcp_f32_e32 v242, v242
	v_rcp_f32_e32 v243, v243
	v_pk_mul_f32 v[244:245], v[236:237], v[244:245]
	v_pk_mul_f32 v[246:247], v[238:239], v[246:247]
	v_pk_mul_f32 v[248:249], v[240:241], v[248:249]
	v_pk_mul_f32 v[250:251], v[242:243], v[250:251]
	v_pk_mul_f32 v[24:25], v[24:25], v[244:245]
	v_pk_mul_f32 v[26:27], v[26:27], v[246:247]
	v_pk_mul_f32 v[20:21], v[20:21], v[248:249]
	v_pk_mul_f32 v[22:23], v[22:23], v[250:251]
	s_nop 0
	s_waitcnt vmcnt(2)
	v_lshlrev_b32_e32 v236, 16, v180
	v_and_b32_e32 v237, 0xffff0000, v180
	v_lshlrev_b32_e32 v238, 16, v181
	v_and_b32_e32 v239, 0xffff0000, v181
	v_lshlrev_b32_e32 v240, 16, v182
	v_and_b32_e32 v241, 0xffff0000, v182
	v_lshlrev_b32_e32 v242, 16, v183
	v_and_b32_e32 v243, 0xffff0000, v183
	v_lshlrev_b32_e32 v244, 16, v184
	v_and_b32_e32 v245, 0xffff0000, v184
	v_lshlrev_b32_e32 v246, 16, v185
	v_and_b32_e32 v247, 0xffff0000, v185
	v_lshlrev_b32_e32 v248, 16, v186
	v_and_b32_e32 v249, 0xffff0000, v186
	v_lshlrev_b32_e32 v250, 16, v187
	v_and_b32_e32 v251, 0xffff0000, v187
	v_rcp_f32_e32 v236, v236
	v_rcp_f32_e32 v237, v237
	v_rcp_f32_e32 v238, v238
	v_rcp_f32_e32 v239, v239
	v_rcp_f32_e32 v240, v240
	v_rcp_f32_e32 v241, v241
	v_rcp_f32_e32 v242, v242
	v_rcp_f32_e32 v243, v243
	v_pk_mul_f32 v[244:245], v[236:237], v[244:245]
	v_pk_mul_f32 v[246:247], v[238:239], v[246:247]
	v_pk_mul_f32 v[248:249], v[240:241], v[248:249]
	v_pk_mul_f32 v[250:251], v[242:243], v[250:251]
	v_pk_mul_f32 v[16:17], v[16:17], v[244:245]
	v_pk_mul_f32 v[18:19], v[18:19], v[246:247]
	v_pk_mul_f32 v[12:13], v[12:13], v[248:249]
	v_pk_mul_f32 v[14:15], v[14:15], v[250:251]
	s_nop 0
	s_waitcnt vmcnt(0)
	v_lshlrev_b32_e32 v236, 16, v188
	v_and_b32_e32 v237, 0xffff0000, v188
	v_lshlrev_b32_e32 v238, 16, v189
	v_and_b32_e32 v239, 0xffff0000, v189
	v_lshlrev_b32_e32 v240, 16, v190
	v_and_b32_e32 v241, 0xffff0000, v190
	v_lshlrev_b32_e32 v242, 16, v191
	v_and_b32_e32 v243, 0xffff0000, v191
	v_lshlrev_b32_e32 v244, 16, v192
	v_and_b32_e32 v245, 0xffff0000, v192
	v_lshlrev_b32_e32 v246, 16, v193
	v_and_b32_e32 v247, 0xffff0000, v193
	v_lshlrev_b32_e32 v248, 16, v194
	v_and_b32_e32 v249, 0xffff0000, v194
	v_lshlrev_b32_e32 v250, 16, v195
	v_and_b32_e32 v251, 0xffff0000, v195
	v_rcp_f32_e32 v236, v236
	v_rcp_f32_e32 v237, v237
	v_rcp_f32_e32 v238, v238
	v_rcp_f32_e32 v239, v239
	v_rcp_f32_e32 v240, v240
	v_rcp_f32_e32 v241, v241
	v_rcp_f32_e32 v242, v242
	v_rcp_f32_e32 v243, v243
	v_pk_mul_f32 v[244:245], v[236:237], v[244:245]
	v_pk_mul_f32 v[246:247], v[238:239], v[246:247]
	v_pk_mul_f32 v[248:249], v[240:241], v[248:249]
	v_pk_mul_f32 v[250:251], v[242:243], v[250:251]
	v_pk_mul_f32 v[8:9], v[8:9], v[244:245]
	v_pk_mul_f32 v[10:11], v[10:11], v[246:247]
	v_pk_mul_f32 v[4:5], v[4:5], v[248:249]
	v_pk_mul_f32 v[6:7], v[6:7], v[250:251]
	s_nop 0
	s_cbranch_vccnz .LBB0_451
	s_barrier
	s_branch .LBB0_451
